# attnB loop: K fragment reads issued after the second MFMA instead of the first
# speedup vs baseline: 1.0065x; 1.0065x over previous
.Lb_loop:
	s_waitcnt lgkmcnt(0)
	v_mfma_f32_32x32x16_bf16 v[32:47], v[192:195], v[224:227], v[32:47]
	v_mfma_f32_32x32x16_bf16 v[48:63], v[196:199], v[224:227], v[48:63]
	ds_read_b128 v[96:99], v146 offset:33280
	ds_read_b128 v[100:103], v147 offset:33280
	ds_read_b128 v[104:107], v148 offset:33280
	ds_read_b128 v[108:111], v149 offset:33280
	v_mfma_f32_32x32x16_bf16 v[16:31], v[200:203], v[224:227], v[16:31]
	v_exp_f32_e32 v240, v80
	v_exp_f32_e32 v241, v81
	v_exp_f32_e32 v242, v82
	v_mfma_f32_32x32x16_bf16 v[0:15], v[204:207], v[224:227], v[0:15]
	v_exp_f32_e32 v243, v83
	v_exp_f32_e32 v244, v84
	v_exp_f32_e32 v245, v85
	s_waitcnt lgkmcnt(0)
	v_mfma_f32_32x32x16_bf16 v[112:127], v[96:99], v[128:131], v[64:79]
	ds_read_b128 v[96:99], v146 offset:37376
	ds_read_b64_tr_b16 v[192:193], v179 offset:18688
	ds_read_b64_tr_b16 v[194:195], v179 offset:19200
	v_add_f32_e32 v145, v240, v241
	v_cvt_pk_bf16_f32 v232, v240, v241
	v_exp_f32_e32 v246, v86
	v_exp_f32_e32 v247, v87
	v_mfma_f32_32x32x16_bf16 v[112:127], v[100:103], v[132:135], v[112:127]
	ds_read_b128 v[100:103], v147 offset:37376
	ds_read_b64_tr_b16 v[196:197], v179 offset:22848
	ds_read_b64_tr_b16 v[198:199], v179 offset:23360
	s_add_i32 s0, s50, 0xffff8000
	s_and_b32 s0, s0, 0x1f8000
	s_lshl_b32 s4, s0, 1
	s_add_i32 m0, s41, 0x18600
	s_nop 0
	buffer_load_dwordx4 v250, s[8:11], s4 offen lds
	s_add_i32 m0, s41, 0x1a600
	s_nop 0
	buffer_load_dwordx4 v250, s[8:11], s4 offen offset:128 lds
	v_add_f32_e32 v145, v145, v242
	v_add_f32_e32 v145, v145, v243
	v_cvt_pk_bf16_f32 v233, v242, v243
	v_exp_f32_e32 v240, v88
	v_mfma_f32_32x32x16_bf16 v[112:127], v[104:107], v[136:139], v[112:127]
	ds_read_b128 v[104:107], v148 offset:37376
	ds_read_b64_tr_b16 v[200:201], v179 offset:27008
	ds_read_b64_tr_b16 v[202:203], v179 offset:27520
	v_exp_f32_e32 v241, v89
	v_add_f32_e32 v145, v145, v244
	v_add_f32_e32 v145, v145, v245
	v_cvt_pk_bf16_f32 v234, v244, v245
	v_exp_f32_e32 v242, v90
	v_mfma_f32_32x32x16_bf16 v[112:127], v[108:111], v[140:143], v[112:127]
	ds_read_b128 v[108:111], v149 offset:37376
	ds_read_b64_tr_b16 v[204:205], v179 offset:31168
	ds_read_b64_tr_b16 v[206:207], v179 offset:31680
	s_add_i32 m0, s43, 0x18600
	s_nop 0
	buffer_load_dwordx4 v251, s[12:15], s4 offen lds
	s_add_i32 m0, s43, 0x1a600
	s_nop 0
	buffer_load_dwordx4 v251, s[12:15], s4 offen offset:128 lds
	v_exp_f32_e32 v243, v91
	v_add_f32_e32 v145, v145, v246
	v_add_f32_e32 v145, v145, v247
	v_cvt_pk_bf16_f32 v235, v246, v247
	v_mfma_f32_32x32x16_bf16 v[32:47], v[208:211], v[228:231], v[32:47]
	ds_read_b64_tr_b16 v[208:209], v179 offset:19712
	ds_read_b64_tr_b16 v[210:211], v179 offset:20224
	v_exp_f32_e32 v244, v92
	v_exp_f32_e32 v245, v93
	v_add_f32_e32 v145, v145, v240
	v_add_f32_e32 v145, v145, v241
	v_mfma_f32_32x32x16_bf16 v[48:63], v[212:215], v[228:231], v[48:63]
	ds_read_b64_tr_b16 v[212:213], v179 offset:23872
	ds_read_b64_tr_b16 v[214:215], v179 offset:24384
	v_cvt_pk_bf16_f32 v236, v240, v241
	v_exp_f32_e32 v246, v94
	v_exp_f32_e32 v247, v95
	v_mfma_f32_32x32x16_bf16 v[16:31], v[216:219], v[228:231], v[16:31]
	ds_read_b64_tr_b16 v[216:217], v179 offset:28032
	ds_read_b64_tr_b16 v[218:219], v179 offset:28544
	v_add_f32_e32 v145, v145, v242
	v_add_f32_e32 v145, v145, v243
	v_cvt_pk_bf16_f32 v237, v242, v243
	v_add_f32_e32 v145, v145, v244
	v_add_f32_e32 v145, v145, v245
	v_cvt_pk_bf16_f32 v238, v244, v245
	v_mfma_f32_32x32x16_bf16 v[0:15], v[220:223], v[228:231], v[0:15]
	ds_read_b64_tr_b16 v[220:221], v179 offset:32192
	ds_read_b64_tr_b16 v[222:223], v179 offset:32704
	v_add_f32_e32 v145, v145, v246
	v_add_f32_e32 v249, v145, v247
	v_cvt_pk_bf16_f32 v239, v246, v247
	v_add_f32_e32 v249, v248, v249
	v_cmp_lt_f32_e32 vcc, s3, v249
	v_add_f32_e32 v191, v191, v249
	s_waitcnt lgkmcnt(8)
	v_mfma_f32_32x32x16_bf16 v[80:95], v[96:99], v[128:131], v[64:79]
	v_exp_f32_e32 v240, v112
	v_exp_f32_e32 v241, v113
	v_mfma_f32_32x32x16_bf16 v[80:95], v[100:103], v[132:135], v[80:95]
	v_exp_f32_e32 v242, v114
	v_exp_f32_e32 v243, v115
	v_exp_f32_e32 v244, v116
	v_mfma_f32_32x32x16_bf16 v[80:95], v[104:107], v[136:139], v[80:95]
	v_exp_f32_e32 v245, v117
	v_add_f32_e32 v145, v240, v241
	v_cvt_pk_bf16_f32 v224, v240, v241
	v_mfma_f32_32x32x16_bf16 v[80:95], v[108:111], v[140:143], v[80:95]
	v_exp_f32_e32 v246, v118
	v_exp_f32_e32 v247, v119
	v_mfma_f32_32x32x16_bf16 v[32:47], v[192:195], v[232:235], v[32:47]
	ds_read_b64_tr_b16 v[192:193], v180 offset:0
	ds_read_b64_tr_b16 v[194:195], v180 offset:512
	v_add_f32_e32 v145, v145, v242
	v_add_f32_e32 v145, v145, v243
	v_cvt_pk_bf16_f32 v225, v242, v243
	v_exp_f32_e32 v240, v120
	v_mfma_f32_32x32x16_bf16 v[48:63], v[196:199], v[232:235], v[48:63]
	ds_read_b64_tr_b16 v[196:197], v180 offset:4160
	ds_read_b64_tr_b16 v[198:199], v180 offset:4672
	v_exp_f32_e32 v241, v121
	v_add_f32_e32 v145, v145, v244
	v_add_f32_e32 v145, v145, v245
	v_cvt_pk_bf16_f32 v226, v244, v245
	v_mfma_f32_32x32x16_bf16 v[16:31], v[200:203], v[232:235], v[16:31]
	ds_read_b64_tr_b16 v[200:201], v180 offset:8320
	ds_read_b64_tr_b16 v[202:203], v180 offset:8832
	v_exp_f32_e32 v242, v122
	v_exp_f32_e32 v243, v123
	v_mfma_f32_32x32x16_bf16 v[0:15], v[204:207], v[232:235], v[0:15]
	ds_read_b64_tr_b16 v[204:205], v180 offset:12480
	ds_read_b64_tr_b16 v[206:207], v180 offset:12992
	v_add_f32_e32 v145, v145, v246
	v_add_f32_e32 v145, v145, v247
	v_cvt_pk_bf16_f32 v227, v246, v247
	v_exp_f32_e32 v244, v124
	s_waitcnt lgkmcnt(8)
	v_mfma_f32_32x32x16_bf16 v[32:47], v[208:211], v[236:239], v[32:47]
	ds_read_b64_tr_b16 v[208:209], v180 offset:1024
	ds_read_b64_tr_b16 v[210:211], v180 offset:1536
	v_exp_f32_e32 v245, v125
	v_add_f32_e32 v145, v145, v240
	v_add_f32_e32 v145, v145, v241
	v_mfma_f32_32x32x16_bf16 v[48:63], v[212:215], v[236:239], v[48:63]
	ds_read_b64_tr_b16 v[212:213], v180 offset:5184
	ds_read_b64_tr_b16 v[214:215], v180 offset:5696
	v_cvt_pk_bf16_f32 v228, v240, v241
	v_exp_f32_e32 v246, v126
	v_exp_f32_e32 v247, v127
	v_mfma_f32_32x32x16_bf16 v[16:31], v[216:219], v[236:239], v[16:31]
	ds_read_b64_tr_b16 v[216:217], v180 offset:9344
	ds_read_b64_tr_b16 v[218:219], v180 offset:9856
	v_add_f32_e32 v145, v145, v242
	v_add_f32_e32 v145, v145, v243
	v_cvt_pk_bf16_f32 v229, v242, v243
	v_add_f32_e32 v145, v145, v244
	v_mfma_f32_32x32x16_bf16 v[0:15], v[220:223], v[236:239], v[0:15]
	ds_read_b64_tr_b16 v[220:221], v180 offset:13504
	ds_read_b64_tr_b16 v[222:223], v180 offset:14016
	v_add_f32_e32 v145, v145, v245
	v_cvt_pk_bf16_f32 v230, v244, v245
	v_add_f32_e32 v145, v145, v246
	v_add_f32_e32 v248, v145, v247
	v_cvt_pk_bf16_f32 v231, v246, v247
	s_cbranch_vccz .Lb_cont0
	s_branch .Lb_rare0
.Lb_cont0:
	s_waitcnt vmcnt(4)
	s_barrier
	s_waitcnt lgkmcnt(0)
	v_mfma_f32_32x32x16_bf16 v[32:47], v[192:195], v[224:227], v[32:47]
	v_mfma_f32_32x32x16_bf16 v[48:63], v[196:199], v[224:227], v[48:63]
	ds_read_b128 v[96:99], v150 offset:0
	ds_read_b128 v[100:103], v151 offset:0
	ds_read_b128 v[104:107], v152 offset:0
	ds_read_b128 v[108:111], v153 offset:0
	v_mfma_f32_32x32x16_bf16 v[16:31], v[200:203], v[224:227], v[16:31]
	v_exp_f32_e32 v240, v80
	v_exp_f32_e32 v241, v81
	v_exp_f32_e32 v242, v82
	v_mfma_f32_32x32x16_bf16 v[0:15], v[204:207], v[224:227], v[0:15]
	v_exp_f32_e32 v243, v83
	v_exp_f32_e32 v244, v84
	v_exp_f32_e32 v245, v85
	s_waitcnt lgkmcnt(0)
	v_mfma_f32_32x32x16_bf16 v[112:127], v[96:99], v[128:131], v[64:79]
	ds_read_b128 v[96:99], v150 offset:4096
	ds_read_b64_tr_b16 v[192:193], v180 offset:2048
	ds_read_b64_tr_b16 v[194:195], v180 offset:2560
	v_add_f32_e32 v145, v240, v241
	v_cvt_pk_bf16_f32 v232, v240, v241
	v_exp_f32_e32 v246, v86
	v_exp_f32_e32 v247, v87
	v_mfma_f32_32x32x16_bf16 v[112:127], v[100:103], v[132:135], v[112:127]
	ds_read_b128 v[100:103], v151 offset:4096
	ds_read_b64_tr_b16 v[196:197], v180 offset:6208
	ds_read_b64_tr_b16 v[198:199], v180 offset:6720
	s_cmp_gt_u32 s6, 59
	s_cbranch_scc1 .Lb_pn0
	s_and_b32 s0, s50, 0x1f8000
	s_lshl_b32 s4, s0, 1
	s_add_i32 m0, s41, 0x0
	s_nop 0
	buffer_load_dwordx4 v250, s[8:11], s4 offen lds
	s_branch .Lb_po0

.Lb_cont1:
	s_waitcnt vmcnt(4)
	s_barrier
	s_waitcnt lgkmcnt(0)
	v_mfma_f32_32x32x16_bf16 v[32:47], v[192:195], v[224:227], v[32:47]
	v_mfma_f32_32x32x16_bf16 v[48:63], v[196:199], v[224:227], v[48:63]
	ds_read_b128 v[96:99], v150 offset:33280
	ds_read_b128 v[100:103], v151 offset:33280
	ds_read_b128 v[104:107], v152 offset:33280
	ds_read_b128 v[108:111], v153 offset:33280
	v_mfma_f32_32x32x16_bf16 v[16:31], v[200:203], v[224:227], v[16:31]
	v_exp_f32_e32 v240, v80
	v_exp_f32_e32 v241, v81
	v_exp_f32_e32 v242, v82
	v_mfma_f32_32x32x16_bf16 v[0:15], v[204:207], v[224:227], v[0:15]
	v_exp_f32_e32 v243, v83
	v_exp_f32_e32 v244, v84
	v_exp_f32_e32 v245, v85
	s_waitcnt lgkmcnt(0)
	v_mfma_f32_32x32x16_bf16 v[112:127], v[96:99], v[128:131], v[64:79]
	ds_read_b128 v[96:99], v150 offset:37376
	ds_read_b64_tr_b16 v[192:193], v182 offset:2048
	ds_read_b64_tr_b16 v[194:195], v182 offset:2560
	v_add_f32_e32 v145, v240, v241
	v_cvt_pk_bf16_f32 v232, v240, v241
	v_exp_f32_e32 v246, v86
	v_exp_f32_e32 v247, v87
	v_mfma_f32_32x32x16_bf16 v[112:127], v[100:103], v[132:135], v[112:127]
	ds_read_b128 v[100:103], v151 offset:37376
	ds_read_b64_tr_b16 v[196:197], v182 offset:6208
	ds_read_b64_tr_b16 v[198:199], v182 offset:6720
	s_cmp_gt_u32 s6, 59
	s_cbranch_scc1 .Lb_pn4
	s_add_i32 s0, s50, 0x8000
	s_and_b32 s0, s0, 0x1f8000
	s_lshl_b32 s4, s0, 1
	s_add_i32 m0, s41, 0x8200
	s_nop 0
	buffer_load_dwordx4 v250, s[8:11], s4 offen lds
	s_branch .Lb_po4

.Lb_cont2:
	s_waitcnt vmcnt(4)
	s_barrier
	s_cmp_gt_u32 s6, 59
	s_cbranch_scc1 .Lb_final
	s_waitcnt lgkmcnt(0)
	v_mfma_f32_32x32x16_bf16 v[32:47], v[192:195], v[224:227], v[32:47]
	v_mfma_f32_32x32x16_bf16 v[48:63], v[196:199], v[224:227], v[48:63]
	ds_read_b128 v[96:99], v146 offset:0
	ds_read_b128 v[100:103], v147 offset:0
	ds_read_b128 v[104:107], v148 offset:0
	ds_read_b128 v[108:111], v149 offset:0
	v_mfma_f32_32x32x16_bf16 v[16:31], v[200:203], v[224:227], v[16:31]
	v_exp_f32_e32 v240, v80
	v_exp_f32_e32 v241, v81
	v_exp_f32_e32 v242, v82
	v_mfma_f32_32x32x16_bf16 v[0:15], v[204:207], v[224:227], v[0:15]
	v_exp_f32_e32 v243, v83
	v_exp_f32_e32 v244, v84
	v_exp_f32_e32 v245, v85
	s_waitcnt lgkmcnt(0)
	v_mfma_f32_32x32x16_bf16 v[112:127], v[96:99], v[128:131], v[64:79]
	ds_read_b128 v[96:99], v146 offset:4096
	ds_read_b64_tr_b16 v[192:193], v182 offset:35328
	ds_read_b64_tr_b16 v[194:195], v182 offset:35840
	v_add_f32_e32 v145, v240, v241
	v_cvt_pk_bf16_f32 v232, v240, v241
	v_exp_f32_e32 v246, v86
	v_exp_f32_e32 v247, v87
	v_mfma_f32_32x32x16_bf16 v[112:127], v[100:103], v[132:135], v[112:127]
	ds_read_b128 v[100:103], v147 offset:4096
	ds_read_b64_tr_b16 v[196:197], v182 offset:39488
	ds_read_b64_tr_b16 v[198:199], v182 offset:40000
	s_add_i32 s0, s50, 0x10000
	s_and_b32 s0, s0, 0x1f8000
	s_lshl_b32 s4, s0, 1
	s_add_i32 m0, s41, 0x10400
	s_nop 0
	buffer_load_dwordx4 v250, s[8:11], s4 offen lds
	s_add_i32 m0, s41, 0x12400
	s_nop 0
	buffer_load_dwordx4 v250, s[8:11], s4 offen offset:128 lds
	v_add_f32_e32 v145, v145, v242
	v_add_f32_e32 v145, v145, v243
	v_cvt_pk_bf16_f32 v233, v242, v243
	v_exp_f32_e32 v240, v88
	v_mfma_f32_32x32x16_bf16 v[112:127], v[104:107], v[136:139], v[112:127]
	ds_read_b128 v[104:107], v148 offset:4096
	ds_read_b64_tr_b16 v[200:201], v182 offset:43648
	ds_read_b64_tr_b16 v[202:203], v182 offset:44160
	v_exp_f32_e32 v241, v89
	v_add_f32_e32 v145, v145, v244
	v_add_f32_e32 v145, v145, v245
	v_cvt_pk_bf16_f32 v234, v244, v245
	v_exp_f32_e32 v242, v90
	v_mfma_f32_32x32x16_bf16 v[112:127], v[108:111], v[140:143], v[112:127]
	ds_read_b128 v[108:111], v149 offset:4096
	ds_read_b64_tr_b16 v[204:205], v182 offset:47808
	ds_read_b64_tr_b16 v[206:207], v182 offset:48320
	s_add_i32 m0, s43, 0x10400
	s_nop 0
	buffer_load_dwordx4 v251, s[12:15], s4 offen lds
	s_add_i32 m0, s43, 0x12400
	s_nop 0
	buffer_load_dwordx4 v251, s[12:15], s4 offen offset:128 lds
	v_exp_f32_e32 v243, v91
	v_add_f32_e32 v145, v145, v246
	v_add_f32_e32 v145, v145, v247
	v_cvt_pk_bf16_f32 v235, v246, v247
	v_mfma_f32_32x32x16_bf16 v[32:47], v[208:211], v[228:231], v[32:47]
	ds_read_b64_tr_b16 v[208:209], v182 offset:36352
	ds_read_b64_tr_b16 v[210:211], v182 offset:36864
	v_exp_f32_e32 v244, v92
	v_exp_f32_e32 v245, v93
	v_add_f32_e32 v145, v145, v240
	v_add_f32_e32 v145, v145, v241
	v_mfma_f32_32x32x16_bf16 v[48:63], v[212:215], v[228:231], v[48:63]
	ds_read_b64_tr_b16 v[212:213], v182 offset:40512
	ds_read_b64_tr_b16 v[214:215], v182 offset:41024
	v_cvt_pk_bf16_f32 v236, v240, v241
	v_exp_f32_e32 v246, v94
	v_exp_f32_e32 v247, v95
	v_mfma_f32_32x32x16_bf16 v[16:31], v[216:219], v[228:231], v[16:31]
	ds_read_b64_tr_b16 v[216:217], v182 offset:44672
	ds_read_b64_tr_b16 v[218:219], v182 offset:45184
	v_add_f32_e32 v145, v145, v242
	v_add_f32_e32 v145, v145, v243
	v_cvt_pk_bf16_f32 v237, v242, v243
	v_add_f32_e32 v145, v145, v244
	v_add_f32_e32 v145, v145, v245
	v_cvt_pk_bf16_f32 v238, v244, v245
	v_mfma_f32_32x32x16_bf16 v[0:15], v[220:223], v[228:231], v[0:15]
	ds_read_b64_tr_b16 v[220:221], v182 offset:48832
	ds_read_b64_tr_b16 v[222:223], v182 offset:49344
	v_add_f32_e32 v145, v145, v246
	v_add_f32_e32 v249, v145, v247
	v_cvt_pk_bf16_f32 v239, v246, v247
	v_add_f32_e32 v249, v248, v249
	v_cmp_lt_f32_e32 vcc, s3, v249
	v_add_f32_e32 v191, v191, v249
	s_waitcnt lgkmcnt(8)
	v_mfma_f32_32x32x16_bf16 v[80:95], v[96:99], v[128:131], v[64:79]
	v_exp_f32_e32 v240, v112
	v_exp_f32_e32 v241, v113
	v_mfma_f32_32x32x16_bf16 v[80:95], v[100:103], v[132:135], v[80:95]
	v_exp_f32_e32 v242, v114
	v_exp_f32_e32 v243, v115
	v_exp_f32_e32 v244, v116
	v_mfma_f32_32x32x16_bf16 v[80:95], v[104:107], v[136:139], v[80:95]
	v_exp_f32_e32 v245, v117
	v_add_f32_e32 v145, v240, v241
	v_cvt_pk_bf16_f32 v224, v240, v241
	v_mfma_f32_32x32x16_bf16 v[80:95], v[108:111], v[140:143], v[80:95]
	v_exp_f32_e32 v246, v118
	v_exp_f32_e32 v247, v119
	v_mfma_f32_32x32x16_bf16 v[32:47], v[192:195], v[232:235], v[32:47]
	ds_read_b64_tr_b16 v[192:193], v179 offset:16640
	ds_read_b64_tr_b16 v[194:195], v179 offset:17152
	v_add_f32_e32 v145, v145, v242
	v_add_f32_e32 v145, v145, v243
	v_cvt_pk_bf16_f32 v225, v242, v243
	v_exp_f32_e32 v240, v120
	v_mfma_f32_32x32x16_bf16 v[48:63], v[196:199], v[232:235], v[48:63]
	ds_read_b64_tr_b16 v[196:197], v179 offset:20800
	ds_read_b64_tr_b16 v[198:199], v179 offset:21312
	v_exp_f32_e32 v241, v121
	v_add_f32_e32 v145, v145, v244
	v_add_f32_e32 v145, v145, v245
	v_cvt_pk_bf16_f32 v226, v244, v245
	v_mfma_f32_32x32x16_bf16 v[16:31], v[200:203], v[232:235], v[16:31]
	ds_read_b64_tr_b16 v[200:201], v179 offset:24960
	ds_read_b64_tr_b16 v[202:203], v179 offset:25472
	v_exp_f32_e32 v242, v122
	v_exp_f32_e32 v243, v123
	v_mfma_f32_32x32x16_bf16 v[0:15], v[204:207], v[232:235], v[0:15]
	ds_read_b64_tr_b16 v[204:205], v179 offset:29120
	ds_read_b64_tr_b16 v[206:207], v179 offset:29632
	v_add_f32_e32 v145, v145, v246
	v_add_f32_e32 v145, v145, v247
	v_cvt_pk_bf16_f32 v227, v246, v247
	v_exp_f32_e32 v244, v124
	s_waitcnt lgkmcnt(8)
	v_mfma_f32_32x32x16_bf16 v[32:47], v[208:211], v[236:239], v[32:47]
	ds_read_b64_tr_b16 v[208:209], v179 offset:17664
	ds_read_b64_tr_b16 v[210:211], v179 offset:18176
	v_exp_f32_e32 v245, v125
	v_add_f32_e32 v145, v145, v240
	v_add_f32_e32 v145, v145, v241
	v_mfma_f32_32x32x16_bf16 v[48:63], v[212:215], v[236:239], v[48:63]
	ds_read_b64_tr_b16 v[212:213], v179 offset:21824
	ds_read_b64_tr_b16 v[214:215], v179 offset:22336
	v_cvt_pk_bf16_f32 v228, v240, v241
	v_exp_f32_e32 v246, v126
	v_exp_f32_e32 v247, v127
	v_mfma_f32_32x32x16_bf16 v[16:31], v[216:219], v[236:239], v[16:31]
	ds_read_b64_tr_b16 v[216:217], v179 offset:25984
	ds_read_b64_tr_b16 v[218:219], v179 offset:26496
	v_add_f32_e32 v145, v145, v242
	v_add_f32_e32 v145, v145, v243
	v_cvt_pk_bf16_f32 v229, v242, v243
	v_add_f32_e32 v145, v145, v244
	v_mfma_f32_32x32x16_bf16 v[0:15], v[220:223], v[236:239], v[0:15]
	ds_read_b64_tr_b16 v[220:221], v179 offset:30144
	ds_read_b64_tr_b16 v[222:223], v179 offset:30656
	v_add_f32_e32 v145, v145, v245
	v_cvt_pk_bf16_f32 v230, v244, v245
	v_add_f32_e32 v145, v145, v246
	v_add_f32_e32 v248, v145, v247
	v_cvt_pk_bf16_f32 v231, v246, v247
	s_cbranch_vccz .Lb_cont3
	s_branch .Lb_rare3
